# late weight-conversion tiles reordered so consecutive waves read adjacent column blocks of the same rows; chunk running-max via DPP prefix scan
# speedup vs baseline: 1.0235x; 1.0017x over previous
.LBB0_805:
	s_abs_i32 s4, s65
	s_mul_hi_u32 s5, s4, s67
	s_mul_i32 s5, s5, s33
	s_lshr_b32 s71, s69, 6
	s_sub_i32 s4, s4, s5
	s_mul_i32 s70, s71, s2
	s_mov_b32 s98, s2
	s_ashr_i32 s2, s65, 31
	s_sub_i32 s5, s4, s33
	s_cmp_ge_u32 s4, s33
	s_cselect_b32 s4, s5, s4
	s_sub_i32 s5, s4, s33
	s_cmp_ge_u32 s4, s33
	s_cselect_b32 s4, s5, s4
	s_xor_b32 s4, s4, s2
	s_sub_i32 s2, s2, s4
	v_add_u32_e32 v2, s2, v5
	v_sub_u32_e32 v3, 0, v2
	v_ashrrev_i32_e32 v0, 31, v2
	v_max_i32_e32 v2, v2, v3
	v_mul_hi_u32 v3, v2, s67
	v_mul_lo_u32 v3, v3, s33
	v_sub_u32_e32 v2, v2, v3
	v_subrev_u32_e32 v3, s33, v2
	v_cmp_le_u32_e32 vcc, s33, v2
	s_nop 1
	v_cndmask_b32_e32 v2, v2, v3, vcc
	v_subrev_u32_e32 v3, s33, v2
	v_cmp_le_u32_e32 vcc, s33, v2
	s_nop 1
	v_cndmask_b32_e32 v2, v2, v3, vcc
	v_xor_b32_e32 v4, v2, v0
	v_sub_u32_e32 v77, v4, v0
	v_cmp_gt_i32_e32 vcc, s70, v77
	s_and_saveexec_b64 s[4:5], vcc
	s_cbranch_execz .LBB0_765
	v_sub_co_u32_e64 v2, s[6:7], s68, 4
	s_xor_b64 s[6:7], s[6:7], -1
	s_cmp_gt_u32 s68, 7
	v_cvt_f32_u32_e32 v6, s98
	s_cselect_b64 s[10:11], -1, 0
	s_add_i32 s2, s68, -13
	s_lshr_b32 s21, s68, 1
	s_lshl_b64 s[14:15], s[2:3], 21
	s_and_b32 s2, s68, 1
	s_lshl_b32 s20, s21, 10
	s_lshl_b64 s[12:13], s[12:13], 1
	s_add_u32 s12, s18, s12
	v_readlane_b32 s36, v253, 18
	s_addc_u32 s13, s19, s13
	v_readlane_b32 s44, v253, 26
	v_rcp_iflag_f32_e32 v6, v6
	v_readlane_b32 s40, v253, 22
	v_readlane_b32 s41, v253, 23
	v_readlane_b32 s42, v253, 24
	v_readlane_b32 s43, v253, 25
	v_readlane_b32 s45, v253, 27
	v_readlane_b32 s46, v253, 28
	v_readlane_b32 s47, v253, 29
	v_readlane_b32 s48, v253, 30
	v_readlane_b32 s49, v253, 31
	v_readlane_b32 s50, v253, 32
	v_readlane_b32 s51, v253, 33
	s_add_u32 s14, s44, s14
	s_addc_u32 s15, s45, s15
	v_readlane_b32 s40, v253, 2
	v_readlane_b32 s41, v253, 3
	v_readlane_b32 s42, v253, 4
	v_readlane_b32 s43, v253, 5
	v_readlane_b32 s44, v253, 6
	v_readlane_b32 s45, v253, 7
	v_readlane_b32 s46, v253, 8
	v_readlane_b32 s47, v253, 9
	v_readlane_b32 s48, v253, 10
	v_readlane_b32 s49, v253, 11
	v_readlane_b32 s50, v253, 12
	v_readlane_b32 s51, v253, 13
	v_readlane_b32 s52, v253, 14
	v_readlane_b32 s53, v253, 15
	v_readlane_b32 s54, v253, 16
	v_readlane_b32 s55, v253, 17
	s_mov_b64 s[40:41], s[44:45]
	v_mul_f32_e32 v6, 0x4f7ffffe, v6
	v_readlane_b32 s37, v253, 19
	v_readlane_b32 s38, v253, 20
	v_readlane_b32 s39, v253, 21
	s_cmp_eq_u32 s2, 0
	s_mul_i32 s2, s21, 0xb00000
	s_mov_b32 s21, s3
	s_mov_b64 s[42:43], s[46:47]
	s_mov_b64 s[44:45], s[48:49]
	s_mov_b64 s[46:47], s[50:51]
	s_mov_b64 s[48:49], s[52:53]
	s_mov_b64 s[50:51], s[54:55]
	v_cvt_u32_f32_e32 v6, v6
	s_cselect_b32 s23, s47, s39
	s_cselect_b32 s22, s46, s38
	s_cselect_b32 s26, s43, s51
	s_cselect_b32 s27, s42, s50
	s_cselect_b32 s28, s45, s37
	s_cselect_b32 s29, s44, s36
	s_cselect_b32 s24, s41, s49
	s_cselect_b32 s25, s40, s48
	s_lshl_b64 s[20:21], s[20:21], 2
	s_add_u32 s34, s25, s20
	s_addc_u32 s35, s24, s21
	s_sub_i32 s20, 0, s98
	v_lshrrev_b32_e32 v2, 1, v2
	v_mul_lo_u32 v7, s20, v6
	v_mul_hi_u32 v3, v2, s64
	v_mul_lo_u32 v2, v2, s64
	v_mul_hi_u32 v7, v6, v7
	s_lshl_b32 s20, s98, 6
	v_lshlrev_b32_e32 v4, 6, v4
	v_lshlrev_b32_e32 v0, 6, v0
	v_lshl_add_u64 v[2:3], s[22:23], 0, v[2:3]
	v_add_u32_e32 v78, v6, v7
	s_sub_i32 s22, 0, s20
	v_sub_u32_e32 v4, v4, v0
	s_mov_b64 s[36:37], 0
	s_branch .LBB0_808

.LBB0_808:
	v_sub_u32_e32 v6, 0, v77
	v_max_i32_e32 v6, v77, v6
	v_mul_hi_u32 v7, v6, v78
	v_mul_lo_u32 v8, v7, s98
	v_sub_u32_e32 v6, v6, v8
	v_add_u32_e32 v8, 1, v7
	v_cmp_le_u32_e32 vcc, s98, v6
	v_ashrrev_i32_e32 v0, 31, v77
	s_nop 0
	v_cndmask_b32_e32 v7, v7, v8, vcc
	v_subrev_u32_e32 v8, s98, v6
	v_cndmask_b32_e32 v6, v6, v8, vcc
	v_add_u32_e32 v8, 1, v7
	v_cmp_le_u32_e32 vcc, s98, v6
	s_nop 1
	v_cndmask_b32_e32 v6, v7, v8, vcc
	v_xor_b32_e32 v6, v6, v0
	v_sub_u32_e32 v8, v6, v0
	v_mul_lo_u32 v9, v8, s22
	v_add_u32_e32 v9, v9, v4
	v_or_b32_e32 v6, v9, v178
	s_and_b64 vcc, exec, s[6:7]
	s_cbranch_vccz .LBB0_814
	s_and_b64 vcc, exec, s[10:11]
	s_cbranch_vccz .LBB0_815
	s_cmp_lt_i32 s68, 11
	s_mov_b64 s[56:57], 0
	s_cbranch_scc1 .LBB0_816
	s_cmp_gt_i32 s68, 11
	s_cbranch_scc0 .LBB0_819
	s_cmp_eq_u32 s68, 12
	s_cbranch_scc0 .LBB0_963
	v_lshlrev_b32_e32 v0, 1, v6
	v_lshrrev_b32_e32 v7, 2, v9
	v_and_b32_e32 v0, 0xc0, v0
	v_and_b32_e32 v7, 32, v7
	v_and_b32_e32 v10, 0xffffff1f, v6
	s_movk_i32 s20, 0x300
	v_or3_b32 v0, v7, v10, v0
	v_cmp_gt_i32_e32 vcc, s20, v6
	v_readlane_b32 s40, v253, 40
	v_readlane_b32 s54, v253, 54
	v_cndmask_b32_e32 v10, v6, v0, vcc
	v_ashrrev_i32_e32 v11, 31, v10
	v_readlane_b32 s55, v253, 55
	v_lshl_add_u64 v[30:31], v[10:11], 2, s[72:73]
	s_mov_b64 s[58:59], 0
	s_mov_b64 s[38:39], s[54:55]
	v_readlane_b32 s41, v253, 41
	v_readlane_b32 s42, v253, 42
	v_readlane_b32 s43, v253, 43
	v_readlane_b32 s44, v253, 44
	v_readlane_b32 s45, v253, 45
	v_readlane_b32 s46, v253, 46
	v_readlane_b32 s47, v253, 47
	v_readlane_b32 s48, v253, 48
	v_readlane_b32 s49, v253, 49
	v_readlane_b32 s50, v253, 50
	v_readlane_b32 s51, v253, 51
	v_readlane_b32 s52, v253, 52
	v_readlane_b32 s53, v253, 53
	s_mov_b64 s[42:43], 0x600
	s_branch .LBB0_821

.LBB0_833:
	v_lshlrev_b32_e32 v8, 6, v8
	v_cmp_ne_u64_e32 vcc, 0, v[30:31]
	v_mov_b32_e32 v11, 0
	v_ashrrev_i32_e32 v9, 31, v8
	v_mov_b32_e32 v10, 0
	s_and_saveexec_b64 s[56:57], vcc
	s_cbranch_execz .LBB0_835
	v_mul_lo_u32 v0, s43, v8
	v_mul_lo_u32 v7, s42, v9
	v_mad_u64_u32 v[12:13], s[20:21], s42, v8, 0
	v_add3_u32 v13, v13, v7, v0
	v_lshl_add_u64 v[12:13], v[12:13], 2, v[30:31]
	global_load_dword v10, v[12:13], off

.LBB0_1234:
	s_or_b64 exec, exec, s[18:19]
	s_lshl_b64 s[18:19], s[16:17], 2
	v_readlane_b32 s14, v252, 12
	s_add_u32 s20, s14, s18
	v_readlane_b32 s14, v252, 13
	s_addc_u32 s21, s14, s19
	v_mov_b64_e32 v[2:3], s[20:21]
	flat_load_dword v90, v[2:3]
	s_waitcnt lgkmcnt(0)
	s_barrier
	s_and_saveexec_b64 s[20:21], s[12:13]
	s_cbranch_execz .LBB0_1244
	s_waitcnt vmcnt(0)
	ds_read_b32 v0, v61 offset:51200
	v_readfirstlane_b32 s14, v176
	s_waitcnt lgkmcnt(0)
	v_mov_b32_e32 v2, v0
	s_nop 1
	v_max_f32_dpp v2, v0, v2 row_shr:1 row_mask:0xf bank_mask:0xf
	v_max_f32_dpp v2, v0, v2 row_shr:2 row_mask:0xf bank_mask:0xf
	v_max_f32_dpp v2, v0, v2 row_shr:3 row_mask:0xf bank_mask:0xf
	s_nop 1
	v_max_f32_dpp v2, v2, v2 row_shr:4 row_mask:0xf bank_mask:0xe
	s_nop 1
	v_max_f32_dpp v2, v2, v2 row_shr:8 row_mask:0xf bank_mask:0xc
	s_nop 1
	v_max_f32_dpp v2, v2, v2 row_bcast:15 row_mask:0xa bank_mask:0xf
	s_nop 1
	v_max_f32_dpp v2, v2, v2 row_bcast:31 row_mask:0xc bank_mask:0xf
	s_nop 1
	v_max_f32_e32 v0, v2, v90
	s_cmp_lt_u32 s14, 64
	s_cbranch_scc1 .Lmx_done
	ds_read_b32 v3, v61 offset:50944
	s_waitcnt lgkmcnt(0)
	v_mov_b32_e32 v8, v3
	s_nop 1
	v_max_f32_dpp v8, v3, v8 row_shr:1 row_mask:0xf bank_mask:0xf
	v_max_f32_dpp v8, v3, v8 row_shr:2 row_mask:0xf bank_mask:0xf
	v_max_f32_dpp v8, v3, v8 row_shr:3 row_mask:0xf bank_mask:0xf
	s_nop 1
	v_max_f32_dpp v8, v8, v8 row_shr:4 row_mask:0xf bank_mask:0xe
	s_nop 1
	v_max_f32_dpp v8, v8, v8 row_shr:8 row_mask:0xf bank_mask:0xc
	s_nop 1
	v_max_f32_dpp v8, v8, v8 row_bcast:15 row_mask:0xa bank_mask:0xf
	s_nop 1
	v_max_f32_dpp v8, v8, v8 row_bcast:31 row_mask:0xc bank_mask:0xf
	s_nop 1
	v_readlane_b32 s17, v8, 63
	s_nop 3
	v_max_f32_e32 v0, s17, v0
.Lmx_done:
	ds_write_b32 v61, v0 offset:51712
